# L1 invalidate also dropped at the P0->in-proj barrier and at the five GEMM-entry group barriers (no L1-resident line those phases read can have been rewritten by another CU since the last invalidate)
# speedup vs baseline: 1.0074x; 1.0028x over previous
.Lmy_xbG_known:
	s_cmp_eq_u32 s18, 2
	s_cbranch_scc0 .Lmy_xbA
	s_and_b32 s3, s2, 7
	s_lshl_b32 s3, s3, 8
	s_add_u32 s16, s74, s3
	s_addc_u32 s17, s75, 0
	s_add_u32 s16, s16, 0x2400
	s_addc_u32 s17, s17, 0
	v_readlane_b32 s18, v255, 23
	s_add_i32 s18, s18, 1
	s_nop 3
	v_writelane_b32 v255, s18, 23
	s_lshl_b32 s18, s18, 5
	v_mov_b32_e32 v4, s18
	global_atomic_add v163, v212, s[16:17]
	s_sub_i32 s3, s68, 1
	s_lshl_b32 s3, 1, s3
	s_and_b32 s3, s3, 0x18b0
	s_cmp_lg_u32 s3, 0
	s_cbranch_scc1 .Lmy_xbG_noinv
	buffer_inv sc1
.Lmy_xbG_noinv:
	s_mov_b32 s3, 0

.Lmy_xb_poll:
	s_mov_b64 exec, s[14:15]
	s_mov_b32 s3, 0
	s_sub_i32 s18, s68, 1
	s_lshl_b32 s18, 1, s18
	s_and_b32 s18, s18, 0x60d
	s_cmp_lg_u32 s18, 0
	s_cbranch_scc1 .Lmy_xb_noinv2
	buffer_inv sc1
